# GEMM main loop: the four redundant s_waitcnt lgkmcnt(0) right behind each barrier removed (the same wait sits in front of the barrier and no LDS op is issued in between)
# speedup vs baseline: 1.0148x; 1.0076x over previous
; #define PG8_STAGE(bufoff, gbase, voff) do { _Pragma("unroll") for (int _i = 0; _i < 2; ++_i) \
;         __builtin_amdgcn_global_load_lds((const unsigned*)((const char*)(gbase) + (voff)[_i]), (LAS unsigned*)(lds + (bufoff) + ldsw + _i * 8192), 16, 0, 0); } while (0)
; #define PG8_LDA(dst, b, h) do { _Pragma("unroll") for (int m = 0; m < 4; ++m) _Pragma("unroll") for (int k = 0; k < 2; ++k) dst[m][k] = *(const LAS bf16x8*)(lds + PG8_SA(b, h) + aoff + m * 2048 + k * 1024); } while (0)
; #define PG8_LDB(dst, b, h) do { _Pragma("unroll") for (int n = 0; n < 2; ++n) _Pragma("unroll") for (int k = 0; k < 2; ++k) dst[n][k] = *(const LAS bf16x8*)(lds + PG8_SB(b, h) + boff + n * 2048 + k * 1024); } while (0)
; #define PG8_MMA(ai, bj, At, Bt) do { __builtin_amdgcn_s_setprio(1); _Pragma("unroll") for (int m = 0; m < 4; ++m) _Pragma("unroll") for (int n = 0; n < 2; ++n) _Pragma("unroll") for (int k = 0; k < 2; ++k) \
;         acc[ai][bj][m][n] = __builtin_amdgcn_mfma_f32_16x16x32_bf16(Bt[n][k], At[m][k], acc[ai][bj][m][n], 0, 0, 0); __builtin_amdgcn_s_setprio(0); } while (0)
; #define PG8_WAIT_V(n) asm volatile("s_waitcnt vmcnt(" #n ")" ::: "memory")
; #define PG8_WAIT_L(n) asm volatile("s_waitcnt lgkmcnt(" #n ")" ::: "memory")
; #define PG8_BAR __builtin_amdgcn_s_barrier()
; #define PG8_SCHED __builtin_amdgcn_sched_barrier(0)
; template <class EpiT>
; __device__ __forceinline__ void gemm_phase(LAS unsigned char* lds, const Gemm g, const StaticOrder& S, const EpiT& E, int wv) {
;     ...
;         for (int t = 0; t < nt; t += 2) {
;             const bool last = (t == nt - 2);
;             const char* a1 = cA + (size_t)(t + 1) * kstep;
;             const char* a2 = last ? nA : cA + (size_t)(t + 2) * kstep; const char* b2 = last ? nB : cB + (size_t)(t + 2) * kstep;
;             const char* a3 = a2 + kstep; const char* b3 = b2 + kstep;
;             PG8_LDB(B0, 0, 0); PG8_LDB(B1, 0, 1); PG8_SCHED; PG8_LDA(At, 0, 0); PG8_STAGE(PG8_SA(1, 1), a1 + hA, voffA);
;             PG8_WAIT_V(8); PG8_WAIT_L(0); PG8_BAR; PG8_MMA(0, 0, At, B0); PG8_MMA(0, 1, At, B1); PG8_BAR; PG8_SCHED;
;             PG8_LDA(At, 0, 1); PG8_STAGE(PG8_SB(0, 0), b2, voffB); PG8_STAGE(PG8_SB(0, 1), b2 + hB, voffB); PG8_STAGE(PG8_SA(0, 0), a2, voffA);
;             PG8_WAIT_V(8); PG8_WAIT_L(0); PG8_BAR; PG8_MMA(1, 0, At, B0); PG8_MMA(1, 1, At, B1); PG8_BAR; PG8_SCHED;
.LBB0_271:
	s_add_i32 s42, s22, 2
	s_add_u32 s43, s0, 0x80
	s_addc_u32 s23, s1, 0
	s_add_i32 s64, 0, 0x10000
	s_cmp_eq_u32 s52, s22
	s_cselect_b32 s23, s19, s23
	s_cselect_b32 s22, s18, s43
	v_add_u32_e32 v0, s64, v234
	s_cselect_b32 s45, s21, s41
	s_cselect_b32 s44, s20, s40
	s_add_i32 s43, 0, 0x14000
	ds_read_b128 v[134:137], v0
	ds_read_b128 v[138:141], v0 offset:1024
	ds_read_b128 v[142:145], v0 offset:2048
	ds_read_b128 v[146:149], v0 offset:3072
	v_add_u32_e32 v0, s43, v234
	ds_read_b128 v[150:153], v0
	ds_read_b128 v[154:157], v0 offset:1024
	ds_read_b128 v[158:161], v0 offset:2048
	ds_read_b128 v[162:165], v0 offset:3072
	s_add_i32 m0, s14, 0xc000
	ds_read_b128 v[166:169], v242
	ds_read_b128 v[170:173], v242 offset:1024
	ds_read_b128 v[174:177], v242 offset:2048
	ds_read_b128 v[178:181], v242 offset:3072
	ds_read_b128 v[204:207], v242 offset:4096
	ds_read_b128 v[208:211], v242 offset:5120
	ds_read_b128 v[212:215], v242 offset:6144
	ds_read_b128 v[216:219], v242 offset:7168
	global_load_lds_dwordx4 v196, s[0:1]
	s_add_i32 m0, s14, 0xe000
	s_nop 0
	global_load_lds_dwordx4 v198, s[0:1]
	s_waitcnt vmcnt(8)
	s_waitcnt lgkmcnt(0)
	s_barrier
	s_setprio 1
	v_mfma_f32_16x16x32_bf16 v[130:133], v[134:137], v[166:169], v[130:133]
	v_mfma_f32_16x16x32_bf16 v[126:129], v[142:145], v[166:169], v[126:129]
	v_mfma_f32_16x16x32_bf16 v[114:117], v[134:137], v[174:177], v[114:117]
	v_mfma_f32_16x16x32_bf16 v[110:113], v[142:145], v[174:177], v[110:113]
	v_mfma_f32_16x16x32_bf16 v[98:101], v[134:137], v[204:207], v[98:101]
	v_mfma_f32_16x16x32_bf16 v[94:97], v[142:145], v[204:207], v[94:97]
	v_mfma_f32_16x16x32_bf16 v[82:85], v[134:137], v[212:215], v[82:85]
	v_mfma_f32_16x16x32_bf16 v[78:81], v[142:145], v[212:215], v[78:81]
	v_mfma_f32_16x16x32_bf16 v[130:133], v[138:141], v[170:173], v[130:133]
	v_mfma_f32_16x16x32_bf16 v[126:129], v[146:149], v[170:173], v[126:129]
	v_mfma_f32_16x16x32_bf16 v[114:117], v[138:141], v[178:181], v[114:117]
	v_mfma_f32_16x16x32_bf16 v[110:113], v[146:149], v[178:181], v[110:113]
	v_mfma_f32_16x16x32_bf16 v[98:101], v[138:141], v[208:211], v[98:101]
	v_mfma_f32_16x16x32_bf16 v[94:97], v[146:149], v[208:211], v[94:97]
	v_mfma_f32_16x16x32_bf16 v[82:85], v[138:141], v[216:219], v[82:85]
	v_mfma_f32_16x16x32_bf16 v[78:81], v[146:149], v[216:219], v[78:81]
	s_setprio 0
	s_setprio 1
	v_mfma_f32_16x16x32_bf16 v[122:125], v[150:153], v[166:169], v[122:125]
	v_mfma_f32_16x16x32_bf16 v[118:121], v[158:161], v[166:169], v[118:121]
	v_mfma_f32_16x16x32_bf16 v[106:109], v[150:153], v[174:177], v[106:109]
	v_mfma_f32_16x16x32_bf16 v[102:105], v[158:161], v[174:177], v[102:105]
	v_mfma_f32_16x16x32_bf16 v[90:93], v[150:153], v[204:207], v[90:93]
	v_mfma_f32_16x16x32_bf16 v[86:89], v[158:161], v[204:207], v[86:89]
	v_mfma_f32_16x16x32_bf16 v[74:77], v[150:153], v[212:215], v[74:77]
	v_mfma_f32_16x16x32_bf16 v[70:73], v[158:161], v[212:215], v[70:73]
	v_mfma_f32_16x16x32_bf16 v[122:125], v[154:157], v[170:173], v[122:125]
	v_mfma_f32_16x16x32_bf16 v[118:121], v[162:165], v[170:173], v[118:121]
	v_mfma_f32_16x16x32_bf16 v[106:109], v[154:157], v[178:181], v[106:109]
	v_mfma_f32_16x16x32_bf16 v[102:105], v[162:165], v[178:181], v[102:105]
	v_mfma_f32_16x16x32_bf16 v[90:93], v[154:157], v[208:211], v[90:93]
	v_mfma_f32_16x16x32_bf16 v[86:89], v[162:165], v[208:211], v[86:89]
	v_mfma_f32_16x16x32_bf16 v[74:77], v[154:157], v[216:219], v[74:77]
	v_mfma_f32_16x16x32_bf16 v[70:73], v[162:165], v[216:219], v[70:73]
	s_setprio 0
	s_barrier
	s_add_i32 s64, s64, s13
	s_mov_b32 m0, s64
	s_add_u32 s36, s44, 0x80
	s_addc_u32 s37, s45, 0
	ds_read_b128 v[166:169], v242 offset:16384
	ds_read_b128 v[170:173], v242 offset:17408
	ds_read_b128 v[174:177], v242 offset:18432
	ds_read_b128 v[178:181], v242 offset:19456
	ds_read_b128 v[204:207], v242 offset:20480
	ds_read_b128 v[208:211], v242 offset:21504
	ds_read_b128 v[212:215], v242 offset:22528
	ds_read_b128 v[216:219], v242 offset:23552
	global_load_lds_dwordx4 v182, s[44:45]
	s_add_i32 m0, s64, 0x2000
	s_add_i32 s43, s43, s13
	global_load_lds_dwordx4 v186, s[44:45]
	s_add_u32 s44, s44, s8
	s_addc_u32 s45, s45, 0
	s_mov_b32 m0, s43
	s_add_u32 s38, s44, 0x80
	s_addc_u32 s39, s45, 0
	global_load_lds_dwordx4 v182, s[44:45]
	s_add_i32 m0, s43, 0x2000
	s_add_u32 s46, s22, 0x80
	s_addc_u32 s47, s23, 0
	global_load_lds_dwordx4 v186, s[44:45]
	s_mov_b32 m0, s14
	s_nop 0
	global_load_lds_dwordx4 v14, s[22:23]
	s_mov_b32 m0, s15
	s_nop 0
	global_load_lds_dwordx4 v184, s[22:23]
	s_waitcnt vmcnt(8)
	s_waitcnt lgkmcnt(0)
	s_barrier
; #define PG8_STAGE(bufoff, gbase, voff) do { _Pragma("unroll") for (int _i = 0; _i < 2; ++_i) \
;         __builtin_amdgcn_global_load_lds((const unsigned*)((const char*)(gbase) + (voff)[_i]), (LAS unsigned*)(lds + (bufoff) + ldsw + _i * 8192), 16, 0, 0); } while (0)
; #define PG8_LDA(dst, b, h) do { _Pragma("unroll") for (int m = 0; m < 4; ++m) _Pragma("unroll") for (int k = 0; k < 2; ++k) dst[m][k] = *(const LAS bf16x8*)(lds + PG8_SA(b, h) + aoff + m * 2048 + k * 1024); } while (0)
; #define PG8_LDB(dst, b, h) do { _Pragma("unroll") for (int n = 0; n < 2; ++n) _Pragma("unroll") for (int k = 0; k < 2; ++k) dst[n][k] = *(const LAS bf16x8*)(lds + PG8_SB(b, h) + boff + n * 2048 + k * 1024); } while (0)
; #define PG8_MMA(ai, bj, At, Bt) do { __builtin_amdgcn_s_setprio(1); _Pragma("unroll") for (int m = 0; m < 4; ++m) _Pragma("unroll") for (int n = 0; n < 2; ++n) _Pragma("unroll") for (int k = 0; k < 2; ++k) \
;         acc[ai][bj][m][n] = __builtin_amdgcn_mfma_f32_16x16x32_bf16(Bt[n][k], At[m][k], acc[ai][bj][m][n], 0, 0, 0); __builtin_amdgcn_s_setprio(0); } while (0)
; #define PG8_WAIT_V(n) asm volatile("s_waitcnt vmcnt(" #n ")" ::: "memory")
; #define PG8_WAIT_L(n) asm volatile("s_waitcnt lgkmcnt(" #n ")" ::: "memory")
; #define PG8_BAR __builtin_amdgcn_s_barrier()
; #define PG8_SCHED __builtin_amdgcn_sched_barrier(0)
; template <class EpiT>
; __device__ __forceinline__ void gemm_phase(LAS unsigned char* lds, const Gemm g, const StaticOrder& S, const EpiT& E, int wv) {
;     ...
;             PG8_WAIT_V(8); PG8_WAIT_L(0); PG8_BAR; PG8_MMA(1, 0, At, B0); PG8_MMA(1, 1, At, B1); PG8_BAR; PG8_SCHED;
;             PG8_LDB(B0, 1, 0); PG8_LDB(B1, 1, 1); PG8_SCHED; PG8_LDA(At, 1, 0); PG8_STAGE(PG8_SA(0, 1), a2 + hA, voffA);
;             PG8_WAIT_V(8); PG8_WAIT_L(0); PG8_BAR; PG8_MMA(0, 0, At, B0); PG8_MMA(0, 1, At, B1); PG8_BAR; PG8_SCHED;
	s_setprio 1
	v_mfma_f32_16x16x32_bf16 v[66:69], v[134:137], v[166:169], v[66:69]
	v_mfma_f32_16x16x32_bf16 v[62:65], v[142:145], v[166:169], v[62:65]
	v_mfma_f32_16x16x32_bf16 v[50:53], v[134:137], v[174:177], v[50:53]
	v_mfma_f32_16x16x32_bf16 v[46:49], v[142:145], v[174:177], v[46:49]
	v_mfma_f32_16x16x32_bf16 v[34:37], v[134:137], v[204:207], v[34:37]
	v_mfma_f32_16x16x32_bf16 v[30:33], v[142:145], v[204:207], v[30:33]
	v_mfma_f32_16x16x32_bf16 v[18:21], v[134:137], v[212:215], v[18:21]
	v_mfma_f32_16x16x32_bf16 v[10:13], v[142:145], v[212:215], v[10:13]
	v_mfma_f32_16x16x32_bf16 v[66:69], v[138:141], v[170:173], v[66:69]
	v_mfma_f32_16x16x32_bf16 v[62:65], v[146:149], v[170:173], v[62:65]
	v_mfma_f32_16x16x32_bf16 v[50:53], v[138:141], v[178:181], v[50:53]
	v_mfma_f32_16x16x32_bf16 v[46:49], v[146:149], v[178:181], v[46:49]
	v_mfma_f32_16x16x32_bf16 v[34:37], v[138:141], v[208:211], v[34:37]
	v_mfma_f32_16x16x32_bf16 v[30:33], v[146:149], v[208:211], v[30:33]
	v_mfma_f32_16x16x32_bf16 v[18:21], v[138:141], v[216:219], v[18:21]
	v_mfma_f32_16x16x32_bf16 v[10:13], v[146:149], v[216:219], v[10:13]
	s_setprio 0
	s_setprio 1
	v_mfma_f32_16x16x32_bf16 v[58:61], v[150:153], v[166:169], v[58:61]
	v_mfma_f32_16x16x32_bf16 v[54:57], v[158:161], v[166:169], v[54:57]
	v_mfma_f32_16x16x32_bf16 v[42:45], v[150:153], v[174:177], v[42:45]
	v_mfma_f32_16x16x32_bf16 v[38:41], v[158:161], v[174:177], v[38:41]
	v_mfma_f32_16x16x32_bf16 v[26:29], v[150:153], v[204:207], v[26:29]
	v_mfma_f32_16x16x32_bf16 v[22:25], v[158:161], v[204:207], v[22:25]
	v_mfma_f32_16x16x32_bf16 v[6:9], v[150:153], v[212:215], v[6:9]
	v_mfma_f32_16x16x32_bf16 v[2:5], v[158:161], v[212:215], v[2:5]
	v_mfma_f32_16x16x32_bf16 v[58:61], v[154:157], v[170:173], v[58:61]
	v_mfma_f32_16x16x32_bf16 v[54:57], v[162:165], v[170:173], v[54:57]
	v_mfma_f32_16x16x32_bf16 v[42:45], v[154:157], v[178:181], v[42:45]
	v_mfma_f32_16x16x32_bf16 v[38:41], v[162:165], v[178:181], v[38:41]
	v_mfma_f32_16x16x32_bf16 v[26:29], v[154:157], v[208:211], v[26:29]
	v_mfma_f32_16x16x32_bf16 v[22:25], v[162:165], v[208:211], v[22:25]
	v_mfma_f32_16x16x32_bf16 v[6:9], v[154:157], v[216:219], v[6:9]
	v_mfma_f32_16x16x32_bf16 v[2:5], v[162:165], v[216:219], v[2:5]
	s_setprio 0
	s_barrier
	s_add_i32 s43, 0, 0x18000
	v_add_u32_e32 v0, s43, v234
	s_add_i32 s44, 0, 0x1c000
	ds_read_b128 v[134:137], v0
	ds_read_b128 v[138:141], v0 offset:1024
	ds_read_b128 v[142:145], v0 offset:2048
	ds_read_b128 v[146:149], v0 offset:3072
	v_add_u32_e32 v0, s44, v234
	ds_read_b128 v[150:153], v0
	ds_read_b128 v[154:157], v0 offset:1024
	ds_read_b128 v[158:161], v0 offset:2048
	ds_read_b128 v[162:165], v0 offset:3072
	s_add_u32 s22, s22, s4
	s_addc_u32 s23, s23, 0
	s_mov_b32 m0, s88
	ds_read_b128 v[166:169], v242 offset:32768
	ds_read_b128 v[170:173], v242 offset:33792
	ds_read_b128 v[174:177], v242 offset:34816
	ds_read_b128 v[178:181], v242 offset:35840
	ds_read_b128 v[204:207], v242 offset:36864
	ds_read_b128 v[208:211], v242 offset:37888
	ds_read_b128 v[212:215], v242 offset:38912
	ds_read_b128 v[216:219], v242 offset:39936
	global_load_lds_dwordx4 v14, s[22:23]
	s_mov_b32 m0, s89
	s_nop 0
	global_load_lds_dwordx4 v184, s[22:23]
	s_waitcnt vmcnt(8)
	s_waitcnt lgkmcnt(0)
	s_barrier
	s_setprio 1
	v_mfma_f32_16x16x32_bf16 v[130:133], v[134:137], v[166:169], v[130:133]
	v_mfma_f32_16x16x32_bf16 v[126:129], v[142:145], v[166:169], v[126:129]
	v_mfma_f32_16x16x32_bf16 v[114:117], v[134:137], v[174:177], v[114:117]
	v_mfma_f32_16x16x32_bf16 v[110:113], v[142:145], v[174:177], v[110:113]
	v_mfma_f32_16x16x32_bf16 v[98:101], v[134:137], v[204:207], v[98:101]
	v_mfma_f32_16x16x32_bf16 v[94:97], v[142:145], v[204:207], v[94:97]
	v_mfma_f32_16x16x32_bf16 v[82:85], v[134:137], v[212:215], v[82:85]
	v_mfma_f32_16x16x32_bf16 v[78:81], v[142:145], v[212:215], v[78:81]
	v_mfma_f32_16x16x32_bf16 v[130:133], v[138:141], v[170:173], v[130:133]
	v_mfma_f32_16x16x32_bf16 v[126:129], v[146:149], v[170:173], v[126:129]
	v_mfma_f32_16x16x32_bf16 v[114:117], v[138:141], v[178:181], v[114:117]
	v_mfma_f32_16x16x32_bf16 v[110:113], v[146:149], v[178:181], v[110:113]
	v_mfma_f32_16x16x32_bf16 v[98:101], v[138:141], v[208:211], v[98:101]
	v_mfma_f32_16x16x32_bf16 v[94:97], v[146:149], v[208:211], v[94:97]
	v_mfma_f32_16x16x32_bf16 v[82:85], v[138:141], v[216:219], v[82:85]
	v_mfma_f32_16x16x32_bf16 v[78:81], v[146:149], v[216:219], v[78:81]
	s_setprio 0
	s_setprio 1
	v_mfma_f32_16x16x32_bf16 v[122:125], v[150:153], v[166:169], v[122:125]
	v_mfma_f32_16x16x32_bf16 v[118:121], v[158:161], v[166:169], v[118:121]
	v_mfma_f32_16x16x32_bf16 v[106:109], v[150:153], v[174:177], v[106:109]
	v_mfma_f32_16x16x32_bf16 v[102:105], v[158:161], v[174:177], v[102:105]
	v_mfma_f32_16x16x32_bf16 v[90:93], v[150:153], v[204:207], v[90:93]
	v_mfma_f32_16x16x32_bf16 v[86:89], v[158:161], v[204:207], v[86:89]
	v_mfma_f32_16x16x32_bf16 v[74:77], v[150:153], v[212:215], v[74:77]
	v_mfma_f32_16x16x32_bf16 v[70:73], v[158:161], v[212:215], v[70:73]
	v_mfma_f32_16x16x32_bf16 v[122:125], v[154:157], v[170:173], v[122:125]
	v_mfma_f32_16x16x32_bf16 v[118:121], v[162:165], v[170:173], v[118:121]
	v_mfma_f32_16x16x32_bf16 v[106:109], v[154:157], v[178:181], v[106:109]
	v_mfma_f32_16x16x32_bf16 v[102:105], v[162:165], v[178:181], v[102:105]
	v_mfma_f32_16x16x32_bf16 v[90:93], v[154:157], v[208:211], v[90:93]
	v_mfma_f32_16x16x32_bf16 v[86:89], v[162:165], v[208:211], v[86:89]
	v_mfma_f32_16x16x32_bf16 v[74:77], v[154:157], v[216:219], v[74:77]
	v_mfma_f32_16x16x32_bf16 v[70:73], v[162:165], v[216:219], v[70:73]
	s_setprio 0
	s_barrier
; #define PG8_STAGE(bufoff, gbase, voff) do { _Pragma("unroll") for (int _i = 0; _i < 2; ++_i) \
;         __builtin_amdgcn_global_load_lds((const unsigned*)((const char*)(gbase) + (voff)[_i]), (LAS unsigned*)(lds + (bufoff) + ldsw + _i * 8192), 16, 0, 0); } while (0)
; #define PG8_LDA(dst, b, h) do { _Pragma("unroll") for (int m = 0; m < 4; ++m) _Pragma("unroll") for (int k = 0; k < 2; ++k) dst[m][k] = *(const LAS bf16x8*)(lds + PG8_SA(b, h) + aoff + m * 2048 + k * 1024); } while (0)
; #define PG8_MMA(ai, bj, At, Bt) do { __builtin_amdgcn_s_setprio(1); _Pragma("unroll") for (int m = 0; m < 4; ++m) _Pragma("unroll") for (int n = 0; n < 2; ++n) _Pragma("unroll") for (int k = 0; k < 2; ++k) \
;         acc[ai][bj][m][n] = __builtin_amdgcn_mfma_f32_16x16x32_bf16(Bt[n][k], At[m][k], acc[ai][bj][m][n], 0, 0, 0); __builtin_amdgcn_s_setprio(0); } while (0)
; #define PG8_WAIT_V(n) asm volatile("s_waitcnt vmcnt(" #n ")" ::: "memory")
; #define PG8_WAIT_L(n) asm volatile("s_waitcnt lgkmcnt(" #n ")" ::: "memory")
; #define PG8_BAR __builtin_amdgcn_s_barrier()
; #define PG8_SCHED __builtin_amdgcn_sched_barrier(0)
; template <class EpiT>
; __device__ __forceinline__ void gemm_phase(LAS unsigned char* lds, const Gemm g, const StaticOrder& S, const EpiT& E, int wv) {
;     ...
;             PG8_LDA(At, 1, 1); PG8_STAGE(PG8_SB(1, 0), b3, voffB); PG8_STAGE(PG8_SB(1, 1), b3 + hB, voffB); PG8_STAGE(PG8_SA(1, 0), a3, voffA);
;             PG8_WAIT_V(8); PG8_WAIT_L(0); PG8_BAR; PG8_MMA(1, 0, At, B0); PG8_MMA(1, 1, At, B1); PG8_BAR; PG8_SCHED;
;         }
	s_add_i32 s22, s43, s13
	s_mov_b32 m0, s22
	ds_read_b128 v[166:169], v242 offset:49152
	ds_read_b128 v[170:173], v242 offset:50176
	ds_read_b128 v[174:177], v242 offset:51200
	ds_read_b128 v[178:181], v242 offset:52224
	ds_read_b128 v[204:207], v242 offset:53248
	ds_read_b128 v[208:211], v242 offset:54272
	ds_read_b128 v[212:215], v242 offset:55296
	ds_read_b128 v[216:219], v242 offset:56320
	global_load_lds_dwordx4 v182, s[36:37]
	s_add_i32 m0, s22, 0x2000
	s_add_i32 s22, s44, s13
	global_load_lds_dwordx4 v186, s[36:37]
	s_mov_b32 m0, s22
	s_nop 0
	global_load_lds_dwordx4 v182, s[38:39]
	s_add_i32 m0, s22, 0x2000
	s_nop 0
	global_load_lds_dwordx4 v186, s[38:39]
	s_mov_b32 m0, s72
	s_nop 0
	global_load_lds_dwordx4 v14, s[46:47]
	s_mov_b32 m0, s73
	s_nop 0
	global_load_lds_dwordx4 v184, s[46:47]
	s_waitcnt vmcnt(8)
	s_waitcnt lgkmcnt(0)
	s_barrier
	s_setprio 1
	v_mfma_f32_16x16x32_bf16 v[66:69], v[134:137], v[166:169], v[66:69]
	v_mfma_f32_16x16x32_bf16 v[62:65], v[142:145], v[166:169], v[62:65]
	v_mfma_f32_16x16x32_bf16 v[50:53], v[134:137], v[174:177], v[50:53]
	v_mfma_f32_16x16x32_bf16 v[46:49], v[142:145], v[174:177], v[46:49]
	v_mfma_f32_16x16x32_bf16 v[34:37], v[134:137], v[204:207], v[34:37]
	v_mfma_f32_16x16x32_bf16 v[30:33], v[142:145], v[204:207], v[30:33]
	v_mfma_f32_16x16x32_bf16 v[18:21], v[134:137], v[212:215], v[18:21]
	v_mfma_f32_16x16x32_bf16 v[10:13], v[142:145], v[212:215], v[10:13]
	v_mfma_f32_16x16x32_bf16 v[66:69], v[138:141], v[170:173], v[66:69]
	v_mfma_f32_16x16x32_bf16 v[62:65], v[146:149], v[170:173], v[62:65]
	v_mfma_f32_16x16x32_bf16 v[50:53], v[138:141], v[178:181], v[50:53]
	v_mfma_f32_16x16x32_bf16 v[46:49], v[146:149], v[178:181], v[46:49]
	v_mfma_f32_16x16x32_bf16 v[34:37], v[138:141], v[208:211], v[34:37]
	v_mfma_f32_16x16x32_bf16 v[30:33], v[146:149], v[208:211], v[30:33]
	v_mfma_f32_16x16x32_bf16 v[18:21], v[138:141], v[216:219], v[18:21]
	v_mfma_f32_16x16x32_bf16 v[10:13], v[146:149], v[216:219], v[10:13]
	s_setprio 0
	s_setprio 1
	v_mfma_f32_16x16x32_bf16 v[58:61], v[150:153], v[166:169], v[58:61]
	v_mfma_f32_16x16x32_bf16 v[54:57], v[158:161], v[166:169], v[54:57]
	v_mfma_f32_16x16x32_bf16 v[42:45], v[150:153], v[174:177], v[42:45]
	v_mfma_f32_16x16x32_bf16 v[38:41], v[158:161], v[174:177], v[38:41]
	v_mfma_f32_16x16x32_bf16 v[26:29], v[150:153], v[204:207], v[26:29]
	v_mfma_f32_16x16x32_bf16 v[22:25], v[158:161], v[204:207], v[22:25]
	v_mfma_f32_16x16x32_bf16 v[6:9], v[150:153], v[212:215], v[6:9]
	v_mfma_f32_16x16x32_bf16 v[2:5], v[158:161], v[212:215], v[2:5]
	v_mfma_f32_16x16x32_bf16 v[58:61], v[154:157], v[170:173], v[58:61]
	v_mfma_f32_16x16x32_bf16 v[54:57], v[162:165], v[170:173], v[54:57]
	v_mfma_f32_16x16x32_bf16 v[42:45], v[154:157], v[178:181], v[42:45]
	v_mfma_f32_16x16x32_bf16 v[38:41], v[162:165], v[178:181], v[38:41]
	v_mfma_f32_16x16x32_bf16 v[26:29], v[154:157], v[208:211], v[26:29]
	v_mfma_f32_16x16x32_bf16 v[22:25], v[162:165], v[208:211], v[22:25]
	v_mfma_f32_16x16x32_bf16 v[6:9], v[154:157], v[216:219], v[6:9]
	v_mfma_f32_16x16x32_bf16 v[2:5], v[162:165], v[216:219], v[2:5]
	s_setprio 0
	s_barrier
	s_add_u32 s0, s0, 0x100
	s_addc_u32 s1, s1, 0
	s_add_u32 s40, s40, 0x100
	s_addc_u32 s41, s41, 0
	s_cmp_ge_i32 s42, s81
	s_mov_b32 s22, s42
	s_cbranch_scc0 .LBB0_271
	s_and_b64 vcc, exec, s[16:17]
	s_cbranch_vccnz .LBB0_278
